# NSA selected top: Q-gather addresses as 32-bit lane offsets + SGPR base (v_mad_u32_u24 instead of v_mad_u64_u32 chains)
# baseline (speedup 1.0000x reference)
; __device__ __forceinline__ void nsa_phase(LAS unsigned char* lds, const bf16_t* Q, const bf16_t* KVG, size_t kvg_stride, const bf16_t* kcc, const bf16_t* vcc, const float* G, bf16_t* cat,
;                                           int tid, int lane, int wave) {
;     ...
;             if (br == 1) {
;                 float zs_ = 0.f; asm volatile("" : "+v"(zs_));
;                 int lane_c = lane_u; asm volatile("" : "+v"(lane_c));
;                 const int lr = lane_c & 15, q = lane_c >> 4;
; #pragma unroll
;                 for (int i = 0; i < 13; ++i) { const int e4 = lane_u + 64 * i; if (e4 < 816) *(LAS f32x4*)(Ssel + e4 * 4) = (f32x4){zs_, zs_, zs_, zs_}; }
;                 KVRegs R;
;                 __syncthreads();
;                 int tb = wave * 64 + lane_u; asm volatile("" : "+v"(tb));
;                 kv_fetch(R, gK + (size_t)nbeg * 4096, gV + (size_t)nbeg * 4096, tb, true);
;                 int kc_ = 0;
;                 const GAS bf16_t* Qw = (const GAS bf16_t*)(Qp + (size_t)(16 * wave) * 768);
;                 const unsigned w_own = selw[lr * 4 + q];
;                 for (int n = nbeg; n < nend; ++n) {
;                     LAS bf16_t* Kt = Kb0 + kc_ * 64 * 72; LAS bf16_t* Vt = Vb0 + kc_ * 64 * 72;
;                     kv_commit(R, Kt, Vt, tb, true);
;                     const bool bitn = ((w_own >> (n & 31)) & 1u) != 0u;
;                     const unsigned mask16 = (unsigned)((__builtin_amdgcn_ballot_w64(bitn) >> (16 * (n >> 5))) & 0xFFFFull);
;                     const int ksel = __builtin_popcount(mask16);
;                     const bool act = ((mask16 >> lr) & 1u) != 0u;
;                     if (act && q == 0) slist[__builtin_popcount(mask16 & ((1u << lr) - 1u))] = (unsigned)lr;
;                     asm volatile("s_waitcnt lgkmcnt(0)" ::: "memory");
;                     int jcg[3], rcg[3]; bool vg[3]; bf16x8 qB[3][2]; unsigned sl[3];
; #pragma unroll
;                     for (int gi = 0; gi < 3; ++gi) sl[gi] = slist[((16 * gi + lr) * 43) >> 7];
; #pragma unroll
;                     for (int gi = 0; gi < 3; ++gi) {
;                         const int cg = 16 * gi + lr, idx = (cg * 43) >> 7; rcg[gi] = cg - 3 * idx; vg[gi] = idx < ksel;
;                         jcg[gi] = vg[gi] ? (int)sl[gi] : 0;
;                         const GAS bf16_t* qg = Qw + (jcg[gi] * 768 + rcg[gi] * 64 + 8 * q);
.LBB0_1040:
	s_or_b64 exec, exec, s[2:3]
	s_mov_b64 s[2:3], exec
	v_readlane_b32 s4, v255, 50
	v_readlane_b32 s5, v255, 51
	s_and_b64 s[4:5], s[2:3], s[4:5]
	s_mov_b64 exec, s[4:5]
	ds_write_b128 v215, v[24:27] offset:52224
	s_or_b64 exec, exec, s[2:3]
	s_mov_b64 s[2:3], exec
	v_readlane_b32 s4, v255, 52
	v_readlane_b32 s5, v255, 53
	s_and_b64 s[4:5], s[2:3], s[4:5]
	s_mov_b64 exec, s[4:5]
	ds_write_b128 v215, v[24:27] offset:53248
	s_or_b64 exec, exec, s[2:3]
	s_mov_b64 s[2:3], exec
	v_readlane_b32 s4, v255, 54
	v_readlane_b32 s5, v255, 55
	s_and_b64 s[4:5], s[2:3], s[4:5]
	s_mov_b64 exec, s[4:5]
	ds_write_b128 v215, v[24:27] offset:54272
	s_or_b64 exec, exec, s[2:3]
	s_mov_b64 s[2:3], exec
	v_readlane_b32 s4, v255, 56
	v_readlane_b32 s5, v255, 57
	s_and_b64 s[4:5], s[2:3], s[4:5]
	s_mov_b64 exec, s[4:5]
	ds_write_b128 v215, v[24:27] offset:55296
	s_or_b64 exec, exec, s[2:3]
	s_mov_b64 s[2:3], exec
	v_readlane_b32 s4, v255, 58
	v_readlane_b32 s5, v255, 59
	s_and_b64 s[4:5], s[2:3], s[4:5]
	s_mov_b64 exec, s[4:5]
	ds_write_b128 v215, v[24:27] offset:56320
	s_or_b64 exec, exec, s[2:3]
	s_mov_b64 s[2:3], exec
	v_readlane_b32 s4, v255, 60
	v_readlane_b32 s5, v255, 61
	s_and_b64 s[4:5], s[2:3], s[4:5]
	s_mov_b64 exec, s[4:5]
	ds_write_b128 v215, v[24:27] offset:57344
	s_or_b64 exec, exec, s[2:3]
	s_mov_b64 s[2:3], exec
	v_readlane_b32 s4, v255, 62
	v_readlane_b32 s5, v255, 63
	s_and_b64 s[4:5], s[2:3], s[4:5]
	s_mov_b64 exec, s[4:5]
	ds_write_b128 v215, v[24:27] offset:58368
	s_or_b64 exec, exec, s[2:3]
	v_mov_b32_e32 v33, v207
	s_cmp_lt_i32 s38, s43
	s_waitcnt lgkmcnt(0)
	s_barrier
	s_cbranch_scc0 .LBB0_948
	s_lshl_b64 s[2:3], s[38:39], 13
	s_add_u32 s4, s34, s2
	v_lshlrev_b32_e32 v34, 3, v33
	s_addc_u32 s5, s35, s3
	v_ashrrev_i32_e32 v35, 31, v34
	s_add_u32 s2, s10, s2
	v_lshlrev_b64 v[36:37], 1, v[34:35]
	s_addc_u32 s3, s11, s3
	v_lshl_add_u64 v[24:25], s[4:5], 0, v[36:37]
	v_lshl_add_u64 v[28:29], s[2:3], 0, v[36:37]
	global_load_dwordx4 v[24:27], v[24:25], off
	v_and_b32_e32 v87, 15, v32
	global_load_dwordx4 v[28:31], v[28:29], off
	v_ashrrev_i32_e32 v35, 4, v32
	v_and_b32_e32 v39, 56, v34
	v_cmp_gt_u32_e64 s[68:69], 16, v32
	v_and_b32_e32 v97, -16, v32
	v_bfe_u32 v34, v32, 2, 2
	v_lshlrev_b32_e32 v32, 2, v32
	v_and_b32_e32 v40, 12, v32
	v_mul_u32_u24_e32 v32, 43, v87
	v_lshlrev_b32_e32 v38, 4, v87
	v_lshlrev_b32_e32 v89, 2, v35
	v_readlane_b32 s2, v255, 37
	v_lshrrev_b32_e32 v105, 7, v32
	v_mad_u32_u24 v32, v87, 43, v223
	v_add3_u32 v38, s2, v38, v89
	v_lshrrev_b32_e32 v33, 3, v33
	s_movk_i32 s2, 0x48
	v_lshrrev_b32_e32 v106, 7, v32
	v_mad_u32_u24 v32, v87, 43, v224
	ds_read_b32 v91, v38
	v_mul_lo_u32 v38, v33, s2
	v_or_b32_e32 v34, v89, v34
	s_movk_i32 s2, 0x90
	v_lshrrev_b32_e32 v108, 7, v32
	v_mul_i32_i24_e32 v32, -3, v106
	v_mul_lo_u32 v104, v34, s2
	v_add3_u32 v92, v32, v87, 16
	v_mul_i32_i24_e32 v32, -3, v108
	v_readlane_b32 s2, v255, 43
	v_add3_u32 v96, v32, v87, 32
	v_lshlrev_b32_e64 v33, v87, -1
	v_sub_u32_e32 v32, s2, v89
	s_lshl_b32 s2, s38, 6
	v_subrev_u32_e32 v111, s2, v32
	s_ashr_i32 s3, s38, 31
	s_mov_b32 s2, s38
	v_not_b32_e32 v95, v33
	v_lshlrev_b32_e32 v33, 3, v35
	v_mad_i32_i24 v88, v105, -3, v87
	s_lshl_b64 s[2:3], s[2:3], 13
	v_lshl_add_u32 v90, v88, 6, v33
	v_lshl_add_u32 v94, v92, 6, v33
	v_lshl_add_u32 v98, v96, 6, v33
	v_lshl_add_u64 v[32:33], s[2:3], 0, v[36:37]
	v_lshl_add_u64 v[34:35], s[10:11], 0, v[32:33]
	v_lshl_add_u64 v[32:33], s[34:35], 0, v[32:33]
	v_lshlrev_b32_e64 v93, v87, 1
	v_mul_u32_u24_e32 v99, 0x90, v87
	v_lshl_add_u32 v107, v106, 2, s27
	v_lshl_add_u32 v109, v108, 2, s27
	v_lshl_add_u32 v110, v105, 2, s27
	v_lshl_add_u64 v[100:101], v[34:35], 0, s[22:23]
	v_lshl_add_u64 v[102:103], v[32:33], 0, s[22:23]
	s_mov_b32 s8, 0
	v_lshlrev_b32_e32 v112, 1, v38
	v_lshlrev_b32_e32 v113, 1, v39
	v_lshlrev_b32_e32 v114, 1, v40
	s_waitcnt lgkmcnt(0)
	s_and_b32 s2, s38, 31
	v_bfe_u32 v199, v91, s2, 1
	s_ashr_i32 s2, s38, 1
	v_cmp_ne_u32_e32 vcc, 0, v199
	s_and_b32 s2, s2, -16
	s_lshr_b64 s[2:3], vcc, s2
	v_and_b32_e32 v199, s2, v93
	v_cmp_ne_u32_e32 vcc, 0, v199
	s_and_b32 s4, s2, 0xffff
	s_bcnt1_i32_b32 s100, s4
	s_and_b64 vcc, vcc, s[68:69]
	s_and_saveexec_b64 s[4:5], vcc
	v_and_b32_e32 v199, s2, v95
	v_bcnt_u32_b32 v199, v199, 0
	v_lshl_add_u32 v199, v199, 2, s27
	ds_write_b32 v199, v87
	s_or_b64 exec, exec, s[4:5]
	s_cmp_eq_u32 s100, 0
	s_cbranch_scc1 .Lsp_gdone_pre
	s_waitcnt lgkmcnt(0)
	ds_read_b32 v200, v107
	ds_read_b32 v199, v109
	v_cmp_gt_u32_e64 s[4:5], s100, v105
	v_mov_b32_e32 v196, 0
	s_nop 0
	s_and_saveexec_b64 s[2:3], s[4:5]
	ds_read_b32 v196, v110
	s_or_b64 exec, exec, s[2:3]
	s_waitcnt lgkmcnt(0)
	v_mad_u32_u24 v202, v196, s48, v90
	v_cmp_gt_u32_e64 s[4:5], s100, v106
	v_cmp_gt_u32_e64 vcc, s100, v108
	v_lshlrev_b32_e32 v202, 1, v202
	s_nop 0
	v_cndmask_b32_e64 v197, 0, v200, s[4:5]
	v_cndmask_b32_e64 v198, 0, v199, vcc
	global_load_dwordx4 v[228:231], v202, s[30:31]
	global_load_dwordx4 v[232:235], v202, s[30:31] offset:64
	s_cmp_lt_u32 s100, 6
	s_cbranch_scc1 .Lsp_gdone_pre
	v_mad_u32_u24 v202, v197, s48, v94
	v_lshlrev_b32_e32 v202, 1, v202
	global_load_dwordx4 v[236:239], v202, s[30:31]
	global_load_dwordx4 v[240:243], v202, s[30:31] offset:64
	s_cmp_lt_u32 s100, 11
	s_cbranch_scc1 .Lsp_gdone_pre
	v_mad_u32_u24 v216, v198, s48, v98
	v_lshlrev_b32_e32 v216, 1, v216
	global_load_dwordx4 v[244:247], v216, s[30:31]
	global_load_dwordx4 v[248:251], v216, s[30:31] offset:64

; #define GAS __attribute__((address_space(1)))
; __device__ __forceinline__ void nsa_phase(LAS unsigned char* lds, const bf16_t* Q, const bf16_t* KVG, size_t kvg_stride, const bf16_t* kcc, const bf16_t* vcc, const float* G, bf16_t* cat,
;                                           int tid, int lane, int wave) {
;     ...
;                     int jcg[3], rcg[3]; bool vg[3]; bf16x8 qB[3][2]; unsigned sl[3];
; #pragma unroll
;                     for (int gi = 0; gi < 3; ++gi) sl[gi] = slist[((16 * gi + lr) * 43) >> 7];
; #pragma unroll
;                     for (int gi = 0; gi < 3; ++gi) {
;                         const int cg = 16 * gi + lr, idx = (cg * 43) >> 7; rcg[gi] = cg - 3 * idx; vg[gi] = idx < ksel;
;                         jcg[gi] = vg[gi] ? (int)sl[gi] : 0;
;                         const GAS bf16_t* qg = Qw + (jcg[gi] * 768 + rcg[gi] * 64 + 8 * q);
;                         qB[gi][0] = *(const GAS bf16x8*)qg; qB[gi][1] = *(const GAS bf16x8*)(qg + 32);
;                     }
.Lsp_movs:
	v_mov_b32_e32 v120, v196
	v_mov_b32_e32 v118, v197
	v_mov_b32_e32 v116, v198
	v_mov_b64_e32 v[76:77], v[228:229]
	v_mov_b64_e32 v[78:79], v[230:231]
	v_mov_b64_e32 v[80:81], v[232:233]
	v_mov_b64_e32 v[82:83], v[234:235]
	v_mov_b64_e32 v[40:41], v[236:237]
	v_mov_b64_e32 v[42:43], v[238:239]
	v_mov_b64_e32 v[44:45], v[240:241]
	v_mov_b64_e32 v[46:47], v[242:243]
	v_mov_b64_e32 v[32:33], v[244:245]
	v_mov_b64_e32 v[34:35], v[246:247]
	v_mov_b64_e32 v[36:37], v[248:249]
	v_mov_b64_e32 v[38:39], v[250:251]
	v_cmp_gt_u32_e64 s[76:77], s10, v105
	v_cmp_gt_u32_e64 s[74:75], s10, v106
	v_cmp_gt_u32_e64 s[70:71], s10, v108
	s_cmp_eq_u32 s101, 1
	s_cbranch_scc1 .Lsp_gdone_loop
	s_cmp_eq_u32 s100, 0
	s_cbranch_scc1 .Lsp_gdone_loop
	s_waitcnt lgkmcnt(0)
	ds_read_b32 v200, v107
	ds_read_b32 v199, v109
	v_cmp_gt_u32_e64 s[4:5], s100, v105
	v_mov_b32_e32 v196, 0
	s_nop 0
	s_and_saveexec_b64 s[2:3], s[4:5]
	ds_read_b32 v196, v110
	s_or_b64 exec, exec, s[2:3]
	s_waitcnt lgkmcnt(0)
	v_mad_u32_u24 v202, v196, s48, v90
	v_cmp_gt_u32_e64 s[4:5], s100, v106
	v_cmp_gt_u32_e64 vcc, s100, v108
	v_lshlrev_b32_e32 v202, 1, v202
	s_nop 0
	v_cndmask_b32_e64 v197, 0, v200, s[4:5]
	v_cndmask_b32_e64 v198, 0, v199, vcc
	global_load_dwordx4 v[228:231], v202, s[30:31]
	global_load_dwordx4 v[232:235], v202, s[30:31] offset:64
	s_cmp_lt_u32 s100, 6
	s_cbranch_scc1 .Lsp_gdone_loop
	v_mad_u32_u24 v202, v197, s48, v94
	v_lshlrev_b32_e32 v202, 1, v202
	global_load_dwordx4 v[236:239], v202, s[30:31]
	global_load_dwordx4 v[240:243], v202, s[30:31] offset:64
	s_cmp_lt_u32 s100, 11
	s_cbranch_scc1 .Lsp_gdone_loop
	v_mad_u32_u24 v216, v198, s48, v98
	v_lshlrev_b32_e32 v216, 1, v216
	global_load_dwordx4 v[244:247], v216, s[30:31]
	global_load_dwordx4 v[248:251], v216, s[30:31] offset:64
